# PH1 EpiRope epilogue: cos/sin table loads software-pipelined one group ahead (counted vmcnt, spare VGPRs), loads as global_load
# speedup vs baseline: 1.0064x; 1.0031x over previous
; __device__ __forceinline__ u32x4 pack8(f32x4 a, f32x4 b) { u32x4 w; w.x = pk2(a[0], a[1]); w.y = pk2(a[2], a[3]); w.z = pk2(b[0], b[1]); w.w = pk2(b[2], b[3]); return w; }
;     __device__ __forceinline__ void operator()(const Acc& acc, const pg8::Unit& u, int wid) const {
;     ...
;         if (pn < 8) {
;             const float kmul = pn >= 4 ? 0.0625f : 1.f;
; #pragma unroll
;             for (int ai = 0; ai < 2; ++ai)
; #pragma unroll
;                 for (int mp = 0; mp < 2; ++mp) {
;                     f32x4 c4[2][2], s4[2][2];
; #pragma unroll
;                     for (int mm = 0; mm < 2; ++mm) { const int s = (row0 + ai * 128 + (2 * mp + mm) * 16) & (SEQ - 1);
; #pragma unroll
;                         for (int n = 0; n < 2; ++n) { c4[mm][n] = *(const f32x4*)(cosT + (size_t)s * 128 + colL + 4 * n); s4[mm][n] = *(const f32x4*)(sinT + (size_t)s * 128 + colL + 4 * n); } }
; #pragma unroll
;                     for (int mm = 0; mm < 2; ++mm) { const int m = 2 * mp + mm, row = row0 + ai * 128 + m * 16;
;                         const float ks = __builtin_amdgcn_rsqf(scv[ai * 4 + m] * (1.f / 1024.f) + EPS) * kmul;
;                         f32x4 o1[2], o2[2];
; #pragma unroll
;                         for (int n = 0; n < 2; ++n) { const f32x4 x1 = acc[ai][0][m][n] * ks, x2 = acc[ai][1][m][n] * ks;
;                             o1[n] = x1 * c4[mm][n] - x2 * s4[mm][n]; o2[n] = x2 * c4[mm][n] + x1 * s4[mm][n]; }
;                         bf16_t* p = QK + (size_t)row * 2048 + pn * 256 + colL;
;                         *(u32x4*)p = pack8(o1[0], o1[1]); *(u32x4*)(p + 128) = pack8(o2[0], o2[1]); }
.LBB0_196:
	s_andn2_b64 vcc, exec, s[34:35]
	s_cbranch_vccnz .LBB0_198
	v_lshlrev_b64 v[130:131], 2, v[164:165]
	v_lshlrev_b32_e32 v132, 9, v156
	v_lshl_add_u64 v[128:129], s[10:11], 0, v[130:131]
	v_and_b32_e32 v144, 0x1f9e00, v132
	v_lshl_add_u64 v[132:133], v[128:129], 0, v[144:145]
	v_lshl_add_u64 v[130:131], s[8:9], 0, v[130:131]
	global_load_dwordx4 v[184:187], v[132:133], off
	global_load_dwordx4 v[188:191], v[132:133], off offset:16
	v_lshl_add_u64 v[132:133], v[130:131], 0, v[144:145]
	global_load_dwordx4 v[192:195], v[132:133], off
	global_load_dwordx4 v[196:199], v[132:133], off offset:16
	v_mov_b32_e32 v133, v145
	v_or_b32_e32 v132, 0x2000, v144
	v_lshl_add_u64 v[134:135], v[128:129], 0, v[132:133]
	global_load_dwordx4 v[200:203], v[134:135], off
	global_load_dwordx4 v[204:207], v[134:135], off offset:16
	v_lshl_add_u64 v[132:133], v[130:131], 0, v[132:133]
	global_load_dwordx4 v[208:211], v[132:133], off
	global_load_dwordx4 v[212:215], v[132:133], off offset:16
	v_or_b32_e32 v132, 0x4000, v144
	v_mov_b32_e32 v133, v145
	v_lshl_add_u64 v[134:135], v[128:129], 0, v[132:133]
	global_load_dwordx4 v[220:223], v[134:135], off
	global_load_dwordx4 v[224:227], v[134:135], off offset:16
	v_lshl_add_u64 v[134:135], v[130:131], 0, v[132:133]
	global_load_dwordx4 v[232:235], v[134:135], off
	global_load_dwordx4 v[236:239], v[134:135], off offset:16
	v_or_b32_e32 v132, 0x6000, v144
	v_lshl_add_u64 v[134:135], v[128:129], 0, v[132:133]
	global_load_dwordx4 v[228:231], v[134:135], off
	global_load_dwordx4 v[246:249], v[134:135], off offset:16
	v_lshl_add_u64 v[134:135], v[130:131], 0, v[132:133]
	global_load_dwordx4 v[240:243], v[134:135], off
	global_load_dwordx4 v[250:253], v[134:135], off offset:16
	s_cmp_gt_i32 s93, 3
	s_cselect_b64 vcc, -1, 0
	v_cndmask_b32_e32 v134, 1.0, v175, vcc
	s_lshl_b32 s34, s93, 8
	v_lshlrev_b64 v[132:133], 1, v[164:165]
	s_ashr_i32 s35, s34, 31
	v_mul_f32_e32 v164, v134, v183
	v_lshl_add_u64 v[166:167], s[44:45], 0, v[166:167]
	v_mul_f32_e32 v168, v134, v182
	v_pk_mul_f32 v[124:125], v[124:125], v[164:165] op_sel_hi:[1,0]
	v_pk_mul_f32 v[126:127], v[126:127], v[164:165] op_sel_hi:[1,0]
	v_pk_mul_f32 v[114:115], v[114:115], v[164:165] op_sel_hi:[1,0]
	v_pk_mul_f32 v[112:113], v[112:113], v[164:165] op_sel_hi:[1,0]
	v_pk_mul_f32 v[110:111], v[110:111], v[164:165] op_sel_hi:[1,0]
	v_pk_mul_f32 v[108:109], v[108:109], v[164:165] op_sel_hi:[1,0]
	s_lshl_b64 s[34:35], s[34:35], 1
	v_pk_mul_f32 v[120:121], v[120:121], v[164:165] op_sel_hi:[1,0]
	v_pk_mul_f32 v[122:123], v[122:123], v[164:165] op_sel_hi:[1,0]
	v_pk_mul_f32 v[116:117], v[116:117], v[168:169] op_sel_hi:[1,0]
	v_pk_mul_f32 v[118:119], v[118:119], v[168:169] op_sel_hi:[1,0]
	v_pk_mul_f32 v[164:165], v[102:103], v[168:169] op_sel_hi:[1,0]
	v_pk_mul_f32 v[182:183], v[100:101], v[168:169] op_sel_hi:[1,0]
	v_pk_mul_f32 v[216:217], v[104:105], v[168:169] op_sel_hi:[1,0]
	v_pk_mul_f32 v[106:107], v[106:107], v[168:169] op_sel_hi:[1,0]
	v_pk_mul_f32 v[218:219], v[98:99], v[168:169] op_sel_hi:[1,0]
	v_pk_mul_f32 v[168:169], v[96:97], v[168:169] op_sel_hi:[1,0]
	v_lshl_add_u64 v[96:97], v[166:167], 0, s[34:35]
	v_lshl_add_u64 v[96:97], v[96:97], 0, v[132:133]
	v_ashrrev_i32_e32 v163, 31, v162
	v_ashrrev_i32_e32 v161, 31, v160
	v_ashrrev_i32_e32 v159, 31, v158
	s_waitcnt vmcnt(8)
	v_pk_mul_f32 v[98:99], v[112:113], v[184:185]
	v_pk_mul_f32 v[100:101], v[114:115], v[186:187]
	v_pk_mul_f32 v[102:103], v[124:125], v[184:185]
	v_pk_mul_f32 v[104:105], v[126:127], v[186:187]
	v_pk_mul_f32 v[166:167], v[108:109], v[188:189]
	v_pk_mul_f32 v[184:185], v[110:111], v[190:191]
	v_pk_mul_f32 v[186:187], v[120:121], v[188:189]
	v_pk_mul_f32 v[188:189], v[122:123], v[190:191]
	v_pk_fma_f32 v[100:101], v[126:127], v[194:195], v[100:101] neg_lo:[0,0,1] neg_hi:[0,0,1]
	v_pk_fma_f32 v[98:99], v[124:125], v[192:193], v[98:99] neg_lo:[0,0,1] neg_hi:[0,0,1]
	v_pk_fma_f32 v[104:105], v[114:115], v[194:195], v[104:105]
	v_pk_fma_f32 v[102:103], v[112:113], v[192:193], v[102:103]
	v_pk_fma_f32 v[112:113], v[122:123], v[198:199], v[184:185] neg_lo:[0,0,1] neg_hi:[0,0,1]
	v_pk_fma_f32 v[114:115], v[120:121], v[196:197], v[166:167] neg_lo:[0,0,1] neg_hi:[0,0,1]
	v_pk_fma_f32 v[110:111], v[110:111], v[198:199], v[188:189]
	v_pk_fma_f32 v[108:109], v[108:109], v[196:197], v[186:187]
	v_cvt_pk_bf16_f32 v98, v98, v99
	v_cvt_pk_bf16_f32 v99, v100, v101
	v_cvt_pk_bf16_f32 v100, v114, v115
	v_cvt_pk_bf16_f32 v101, v112, v113
	v_cvt_pk_bf16_f32 v102, v102, v103
	v_cvt_pk_bf16_f32 v103, v104, v105
	v_cvt_pk_bf16_f32 v104, v108, v109
	v_cvt_pk_bf16_f32 v105, v110, v111
	flat_store_dwordx4 v[96:97], v[98:101]
	flat_store_dwordx4 v[96:97], v[102:105] offset:256
	v_pk_mul_f32 v[120:121], v[182:183], v[200:201]
	v_lshlrev_b64 v[98:99], 12, v[162:163]
	v_pk_mul_f32 v[122:123], v[164:165], v[202:203]
	v_pk_mul_f32 v[166:167], v[168:169], v[204:205]
	v_pk_mul_f32 v[184:185], v[218:219], v[206:207]
	v_lshl_add_u64 v[98:99], s[44:45], 0, v[98:99]
	v_pk_mul_f32 v[124:125], v[116:117], v[200:201]
	v_pk_mul_f32 v[126:127], v[118:119], v[202:203]
	v_pk_mul_f32 v[186:187], v[216:217], v[204:205]
	v_pk_mul_f32 v[188:189], v[106:107], v[206:207]
	v_pk_fma_f32 v[108:109], v[118:119], v[210:211], v[122:123] neg_lo:[0,0,1] neg_hi:[0,0,1]
	v_pk_fma_f32 v[110:111], v[116:117], v[208:209], v[120:121] neg_lo:[0,0,1] neg_hi:[0,0,1]
	v_pk_fma_f32 v[106:107], v[106:107], v[214:215], v[184:185] neg_lo:[0,0,1] neg_hi:[0,0,1]
	v_pk_fma_f32 v[116:117], v[216:217], v[212:213], v[166:167] neg_lo:[0,0,1] neg_hi:[0,0,1]
	v_lshl_add_u64 v[98:99], v[98:99], 0, s[34:35]
	v_pk_fma_f32 v[112:113], v[164:165], v[210:211], v[126:127]
; __device__ __forceinline__ u32x4 pack8(f32x4 a, f32x4 b) { u32x4 w; w.x = pk2(a[0], a[1]); w.y = pk2(a[2], a[3]); w.z = pk2(b[0], b[1]); w.w = pk2(b[2], b[3]); return w; }
;     __device__ __forceinline__ void operator()(const Acc& acc, const pg8::Unit& u, int wid) const {
;     ...
;                     for (int mm = 0; mm < 2; ++mm) { const int s = (row0 + ai * 128 + (2 * mp + mm) * 16) & (SEQ - 1);
; #pragma unroll
;                         for (int n = 0; n < 2; ++n) { c4[mm][n] = *(const f32x4*)(cosT + (size_t)s * 128 + colL + 4 * n); s4[mm][n] = *(const f32x4*)(sinT + (size_t)s * 128 + colL + 4 * n); } }
; #pragma unroll
;                     for (int mm = 0; mm < 2; ++mm) { const int m = 2 * mp + mm, row = row0 + ai * 128 + m * 16;
;                         const float ks = __builtin_amdgcn_rsqf(scv[ai * 4 + m] * (1.f / 1024.f) + EPS) * kmul;
;                         f32x4 o1[2], o2[2];
; #pragma unroll
;                         for (int n = 0; n < 2; ++n) { const f32x4 x1 = acc[ai][0][m][n] * ks, x2 = acc[ai][1][m][n] * ks;
;                             o1[n] = x1 * c4[mm][n] - x2 * s4[mm][n]; o2[n] = x2 * c4[mm][n] + x1 * s4[mm][n]; }
;                         bf16_t* p = QK + (size_t)row * 2048 + pn * 256 + colL;
;                         *(u32x4*)p = pack8(o1[0], o1[1]); *(u32x4*)(p + 128) = pack8(o2[0], o2[1]); }
	v_pk_fma_f32 v[114:115], v[182:183], v[208:209], v[124:125]
	v_pk_fma_f32 v[102:103], v[218:219], v[214:215], v[188:189]
	v_pk_fma_f32 v[104:105], v[168:169], v[212:213], v[186:187]
	v_lshl_add_u64 v[118:119], v[98:99], 0, v[132:133]
	v_cvt_pk_bf16_f32 v98, v110, v111
	v_cvt_pk_bf16_f32 v99, v108, v109
	v_cvt_pk_bf16_f32 v100, v116, v117
	v_cvt_pk_bf16_f32 v101, v106, v107
	flat_store_dwordx4 v[118:119], v[98:101]
	s_nop 1
	v_cvt_pk_bf16_f32 v98, v114, v115
	v_cvt_pk_bf16_f32 v99, v112, v113
	v_cvt_pk_bf16_f32 v100, v104, v105
	v_cvt_pk_bf16_f32 v101, v102, v103
	flat_store_dwordx4 v[118:119], v[98:101] offset:256
	v_lshl_add_u32 v216, v156, 7, v176
	v_and_b32_e32 v216, 0x7e780, v216
	v_lshlrev_b32_e32 v216, 2, v216
	v_mov_b32_e32 v217, v145
	v_lshl_add_u64 v[102:103], v[128:129], 0, v[216:217]
	global_load_dwordx4 v[184:187], v[102:103], off
	global_load_dwordx4 v[188:191], v[102:103], off offset:16
	v_lshl_add_u64 v[102:103], v[130:131], 0, v[216:217]
	global_load_dwordx4 v[192:195], v[102:103], off
	global_load_dwordx4 v[196:199], v[102:103], off offset:16
	v_or_b32_e32 v104, 0x2000, v216
	v_mov_b32_e32 v105, v145
	v_lshl_add_u64 v[102:103], v[128:129], 0, v[104:105]
	global_load_dwordx4 v[200:203], v[102:103], off
	global_load_dwordx4 v[208:211], v[102:103], off offset:16
	v_lshl_add_u64 v[102:103], v[130:131], 0, v[104:105]
	global_load_dwordx4 v[204:207], v[102:103], off
	global_load_dwordx4 v[212:215], v[102:103], off offset:16
	v_mul_f32_e32 v144, v134, v181
	v_lshlrev_b64 v[126:127], 12, v[160:161]
	v_mul_f32_e32 v160, v134, v180
	v_pk_mul_f32 v[82:83], v[82:83], v[144:145] op_sel_hi:[1,0]
	v_pk_mul_f32 v[80:81], v[80:81], v[144:145] op_sel_hi:[1,0]
	v_pk_mul_f32 v[78:79], v[78:79], v[144:145] op_sel_hi:[1,0]
	v_pk_mul_f32 v[76:77], v[76:77], v[144:145] op_sel_hi:[1,0]
	v_lshl_add_u64 v[126:127], s[44:45], 0, v[126:127]
	v_pk_mul_f32 v[92:93], v[92:93], v[144:145] op_sel_hi:[1,0]
	v_pk_mul_f32 v[94:95], v[94:95], v[144:145] op_sel_hi:[1,0]
	v_pk_mul_f32 v[88:89], v[88:89], v[144:145] op_sel_hi:[1,0]
	v_pk_mul_f32 v[90:91], v[90:91], v[144:145] op_sel_hi:[1,0]
	v_pk_mul_f32 v[84:85], v[84:85], v[160:161] op_sel_hi:[1,0]
	v_pk_mul_f32 v[86:87], v[86:87], v[160:161] op_sel_hi:[1,0]
	v_pk_mul_f32 v[74:75], v[74:75], v[160:161] op_sel_hi:[1,0]
	v_pk_mul_f32 v[72:73], v[72:73], v[160:161] op_sel_hi:[1,0]
	v_lshl_add_u64 v[126:127], v[126:127], 0, s[34:35]
	v_lshl_add_u64 v[126:127], v[126:127], 0, v[132:133]
	v_pk_mul_f32 v[64:65], v[64:65], v[160:161] op_sel_hi:[1,0]
	v_pk_mul_f32 v[68:69], v[68:69], v[160:161] op_sel_hi:[1,0]
	v_pk_mul_f32 v[66:67], v[66:67], v[160:161] op_sel_hi:[1,0]
	v_pk_mul_f32 v[70:71], v[70:71], v[160:161] op_sel_hi:[1,0]
	s_waitcnt vmcnt(12)
	v_pk_mul_f32 v[166:167], v[80:81], v[220:221]
	v_pk_mul_f32 v[168:169], v[82:83], v[222:223]
	v_pk_mul_f32 v[180:181], v[76:77], v[224:225]
	v_pk_mul_f32 v[182:183], v[78:79], v[226:227]
	v_pk_mul_f32 v[220:221], v[92:93], v[220:221]
	v_pk_mul_f32 v[222:223], v[94:95], v[222:223]
	v_pk_mul_f32 v[224:225], v[88:89], v[224:225]
	v_pk_mul_f32 v[226:227], v[90:91], v[226:227]
	v_pk_mul_f32 v[98:99], v[72:73], v[228:229]
	v_pk_mul_f32 v[100:101], v[74:75], v[230:231]
	v_pk_mul_f32 v[228:229], v[84:85], v[228:229]
	v_pk_mul_f32 v[230:231], v[86:87], v[230:231]
	v_pk_fma_f32 v[94:95], v[94:95], v[234:235], v[168:169] neg_lo:[0,0,1] neg_hi:[0,0,1]
	v_pk_fma_f32 v[92:93], v[92:93], v[232:233], v[166:167] neg_lo:[0,0,1] neg_hi:[0,0,1]
	v_pk_fma_f32 v[90:91], v[90:91], v[238:239], v[182:183] neg_lo:[0,0,1] neg_hi:[0,0,1]
	v_pk_fma_f32 v[88:89], v[88:89], v[236:237], v[180:181] neg_lo:[0,0,1] neg_hi:[0,0,1]
	v_pk_fma_f32 v[82:83], v[82:83], v[234:235], v[222:223]
	v_pk_fma_f32 v[80:81], v[80:81], v[232:233], v[220:221]
	v_pk_fma_f32 v[220:221], v[78:79], v[238:239], v[226:227]
	v_pk_fma_f32 v[78:79], v[76:77], v[236:237], v[224:225]
	v_pk_fma_f32 v[222:223], v[74:75], v[242:243], v[230:231]
	v_pk_fma_f32 v[224:225], v[72:73], v[240:241], v[228:229]
	v_cvt_pk_bf16_f32 v72, v92, v93
	v_cvt_pk_bf16_f32 v73, v94, v95
	v_cvt_pk_bf16_f32 v74, v88, v89
	v_cvt_pk_bf16_f32 v75, v90, v91
	v_cvt_pk_bf16_f32 v76, v80, v81
	v_cvt_pk_bf16_f32 v77, v82, v83
	v_cvt_pk_bf16_f32 v78, v78, v79
	v_cvt_pk_bf16_f32 v79, v220, v221
	flat_store_dwordx4 v[126:127], v[72:75]
	flat_store_dwordx4 v[126:127], v[76:79] offset:256
	v_pk_fma_f32 v[86:87], v[86:87], v[242:243], v[100:101] neg_lo:[0,0,1] neg_hi:[0,0,1]
	v_pk_mul_f32 v[72:73], v[64:65], v[246:247]
	v_pk_mul_f32 v[74:75], v[66:67], v[248:249]
	v_pk_fma_f32 v[72:73], v[68:69], v[250:251], v[72:73] neg_lo:[0,0,1] neg_hi:[0,0,1]
	v_pk_mul_f32 v[68:69], v[68:69], v[246:247]
	v_pk_fma_f32 v[84:85], v[84:85], v[240:241], v[98:99] neg_lo:[0,0,1] neg_hi:[0,0,1]
	v_pk_fma_f32 v[68:69], v[64:65], v[250:251], v[68:69]
	v_lshlrev_b64 v[64:65], 12, v[158:159]
	v_lshl_add_u64 v[64:65], s[44:45], 0, v[64:65]
	v_pk_fma_f32 v[74:75], v[70:71], v[252:253], v[74:75] neg_lo:[0,0,1] neg_hi:[0,0,1]
	v_pk_mul_f32 v[70:71], v[70:71], v[248:249]
	v_lshl_add_u64 v[64:65], v[64:65], 0, s[34:35]
	v_pk_fma_f32 v[70:71], v[66:67], v[252:253], v[70:71]
	v_lshl_add_u64 v[76:77], v[64:65], 0, v[132:133]
	v_cvt_pk_bf16_f32 v64, v84, v85
	v_cvt_pk_bf16_f32 v65, v86, v87
	v_cvt_pk_bf16_f32 v66, v72, v73
	v_cvt_pk_bf16_f32 v67, v74, v75
	flat_store_dwordx4 v[76:77], v[64:67]
	s_nop 1
	v_cvt_pk_bf16_f32 v64, v224, v225
	v_cvt_pk_bf16_f32 v65, v222, v223
	v_cvt_pk_bf16_f32 v66, v68, v69
	v_cvt_pk_bf16_f32 v67, v70, v71
	flat_store_dwordx4 v[76:77], v[64:67] offset:256
	v_lshl_add_u64 v[98:99], s[44:45], 0, v[154:155]
	v_or_b32_e32 v104, 0x4000, v216
	v_mov_b32_e32 v105, v145
; __device__ __forceinline__ u32x4 pack8(f32x4 a, f32x4 b) { u32x4 w; w.x = pk2(a[0], a[1]); w.y = pk2(a[2], a[3]); w.z = pk2(b[0], b[1]); w.w = pk2(b[2], b[3]); return w; }
;     __device__ __forceinline__ void operator()(const Acc& acc, const pg8::Unit& u, int wid) const {
;     ...
;                     for (int mm = 0; mm < 2; ++mm) { const int s = (row0 + ai * 128 + (2 * mp + mm) * 16) & (SEQ - 1);
; #pragma unroll
;                         for (int n = 0; n < 2; ++n) { c4[mm][n] = *(const f32x4*)(cosT + (size_t)s * 128 + colL + 4 * n); s4[mm][n] = *(const f32x4*)(sinT + (size_t)s * 128 + colL + 4 * n); } }
; #pragma unroll
;                     for (int mm = 0; mm < 2; ++mm) { const int m = 2 * mp + mm, row = row0 + ai * 128 + m * 16;
;                         const float ks = __builtin_amdgcn_rsqf(scv[ai * 4 + m] * (1.f / 1024.f) + EPS) * kmul;
;                         f32x4 o1[2], o2[2];
; #pragma unroll
;                         for (int n = 0; n < 2; ++n) { const f32x4 x1 = acc[ai][0][m][n] * ks, x2 = acc[ai][1][m][n] * ks;
;                             o1[n] = x1 * c4[mm][n] - x2 * s4[mm][n]; o2[n] = x2 * c4[mm][n] + x1 * s4[mm][n]; }
;                         bf16_t* p = QK + (size_t)row * 2048 + pn * 256 + colL;
;                         *(u32x4*)p = pack8(o1[0], o1[1]); *(u32x4*)(p + 128) = pack8(o2[0], o2[1]); }
	v_lshl_add_u64 v[106:107], v[128:129], 0, v[104:105]
	global_load_dwordx4 v[220:223], v[106:107], off
	global_load_dwordx4 v[224:227], v[106:107], off offset:16
	v_lshl_add_u64 v[106:107], v[130:131], 0, v[104:105]
	global_load_dwordx4 v[228:231], v[106:107], off
	global_load_dwordx4 v[232:235], v[106:107], off offset:16
	v_or_b32_e32 v104, 0x6000, v216
	v_lshl_add_u64 v[106:107], v[128:129], 0, v[104:105]
	global_load_dwordx4 v[236:239], v[106:107], off
	global_load_dwordx4 v[246:249], v[106:107], off offset:16
	v_lshl_add_u64 v[106:107], v[130:131], 0, v[104:105]
	global_load_dwordx4 v[240:243], v[106:107], off
	global_load_dwordx4 v[250:253], v[106:107], off offset:16
	v_mul_f32_e32 v100, v134, v179
	v_pk_mul_f32 v[54:55], v[54:55], v[100:101] op_sel_hi:[1,0]
	v_pk_mul_f32 v[52:53], v[52:53], v[100:101] op_sel_hi:[1,0]
	v_pk_mul_f32 v[50:51], v[50:51], v[100:101] op_sel_hi:[1,0]
	v_pk_mul_f32 v[48:49], v[48:49], v[100:101] op_sel_hi:[1,0]
	v_pk_mul_f32 v[60:61], v[60:61], v[100:101] op_sel_hi:[1,0]
	v_pk_mul_f32 v[62:63], v[62:63], v[100:101] op_sel_hi:[1,0]
	v_pk_mul_f32 v[56:57], v[56:57], v[100:101] op_sel_hi:[1,0]
	v_pk_mul_f32 v[58:59], v[58:59], v[100:101] op_sel_hi:[1,0]
	v_mul_f32_e32 v102, v134, v178
	v_lshl_add_u64 v[98:99], v[98:99], 0, s[34:35]
	v_lshl_add_u64 v[98:99], v[98:99], 0, v[132:133]
	v_pk_mul_f32 v[38:39], v[38:39], v[102:103] op_sel_hi:[1,0]
	v_pk_mul_f32 v[36:37], v[36:37], v[102:103] op_sel_hi:[1,0]
	v_pk_mul_f32 v[44:45], v[44:45], v[102:103] op_sel_hi:[1,0]
	v_pk_mul_f32 v[46:47], v[46:47], v[102:103] op_sel_hi:[1,0]
	v_pk_mul_f32 v[34:35], v[34:35], v[102:103] op_sel_hi:[1,0]
	v_pk_mul_f32 v[32:33], v[32:33], v[102:103] op_sel_hi:[1,0]
	v_pk_mul_f32 v[40:41], v[40:41], v[102:103] op_sel_hi:[1,0]
	v_pk_mul_f32 v[42:43], v[42:43], v[102:103] op_sel_hi:[1,0]
	v_lshl_add_u64 v[168:169], v[96:97], 0, s[22:23]
	s_waitcnt vmcnt(12)
	v_pk_mul_f32 v[100:101], v[52:53], v[184:185]
	v_pk_mul_f32 v[104:105], v[54:55], v[186:187]
	v_pk_mul_f32 v[106:107], v[48:49], v[188:189]
	v_pk_mul_f32 v[108:109], v[50:51], v[190:191]
	v_pk_mul_f32 v[184:185], v[60:61], v[184:185]
	v_pk_mul_f32 v[186:187], v[62:63], v[186:187]
	v_pk_mul_f32 v[188:189], v[56:57], v[188:189]
	v_pk_mul_f32 v[190:191], v[58:59], v[190:191]
	v_pk_fma_f32 v[62:63], v[62:63], v[194:195], v[104:105] neg_lo:[0,0,1] neg_hi:[0,0,1]
	v_pk_fma_f32 v[60:61], v[60:61], v[192:193], v[100:101] neg_lo:[0,0,1] neg_hi:[0,0,1]
	v_pk_fma_f32 v[58:59], v[58:59], v[198:199], v[108:109] neg_lo:[0,0,1] neg_hi:[0,0,1]
	v_pk_fma_f32 v[56:57], v[56:57], v[196:197], v[106:107] neg_lo:[0,0,1] neg_hi:[0,0,1]
	v_pk_fma_f32 v[54:55], v[54:55], v[194:195], v[186:187]
	v_pk_fma_f32 v[52:53], v[52:53], v[192:193], v[184:185]
	v_pk_fma_f32 v[184:185], v[50:51], v[198:199], v[190:191]
	v_pk_fma_f32 v[186:187], v[48:49], v[196:197], v[188:189]
	v_cvt_pk_bf16_f32 v48, v60, v61
	v_cvt_pk_bf16_f32 v49, v62, v63
	v_cvt_pk_bf16_f32 v50, v56, v57
	v_cvt_pk_bf16_f32 v51, v58, v59
	v_cvt_pk_bf16_f32 v52, v52, v53
	v_cvt_pk_bf16_f32 v53, v54, v55
	v_cvt_pk_bf16_f32 v54, v186, v187
	v_cvt_pk_bf16_f32 v55, v184, v185
	flat_store_dwordx4 v[98:99], v[48:51]
	flat_store_dwordx4 v[98:99], v[52:55] offset:256
	v_mul_f32_e32 v184, v134, v177
	v_pk_mul_f32 v[48:49], v[36:37], v[200:201]
	v_pk_mul_f32 v[50:51], v[38:39], v[202:203]
	v_pk_fma_f32 v[48:49], v[44:45], v[204:205], v[48:49] neg_lo:[0,0,1] neg_hi:[0,0,1]
	v_pk_fma_f32 v[50:51], v[46:47], v[206:207], v[50:51] neg_lo:[0,0,1] neg_hi:[0,0,1]
	v_pk_mul_f32 v[44:45], v[44:45], v[200:201]
	v_pk_mul_f32 v[46:47], v[46:47], v[202:203]
	v_pk_fma_f32 v[36:37], v[36:37], v[204:205], v[44:45]
	v_pk_fma_f32 v[38:39], v[38:39], v[206:207], v[46:47]
	v_pk_mul_f32 v[44:45], v[32:33], v[208:209]
	v_pk_mul_f32 v[46:47], v[34:35], v[210:211]
	v_pk_fma_f32 v[44:45], v[40:41], v[212:213], v[44:45] neg_lo:[0,0,1] neg_hi:[0,0,1]
	v_pk_fma_f32 v[46:47], v[42:43], v[214:215], v[46:47] neg_lo:[0,0,1] neg_hi:[0,0,1]
	v_pk_mul_f32 v[42:43], v[42:43], v[210:211]
	v_pk_mul_f32 v[40:41], v[40:41], v[208:209]
	v_pk_fma_f32 v[42:43], v[34:35], v[214:215], v[42:43]
	v_cvt_pk_bf16_f32 v34, v44, v45
	v_add_co_u32_e32 v44, vcc, s83, v96
	v_pk_fma_f32 v[40:41], v[32:33], v[212:213], v[40:41]
	v_cvt_pk_bf16_f32 v32, v48, v49
	v_cvt_pk_bf16_f32 v33, v50, v51
	v_cvt_pk_bf16_f32 v35, v46, v47
	v_addc_co_u32_e32 v45, vcc, 0, v97, vcc
	v_lshl_add_u64 v[52:53], v[96:97], 0, s[18:19]
	flat_store_dwordx4 v[44:45], v[32:35]
	v_pk_mul_f32 v[16:17], v[16:17], v[184:185] op_sel_hi:[1,0]
	v_pk_mul_f32 v[28:29], v[28:29], v[184:185] op_sel_hi:[1,0]
	v_cvt_pk_bf16_f32 v32, v36, v37
	v_cvt_pk_bf16_f32 v33, v38, v39
	v_cvt_pk_bf16_f32 v34, v40, v41
	v_cvt_pk_bf16_f32 v35, v42, v43
	flat_store_dwordx4 v[52:53], v[32:35] offset:256
	v_pk_mul_f32 v[22:23], v[22:23], v[184:185] op_sel_hi:[1,0]
	v_pk_mul_f32 v[20:21], v[20:21], v[184:185] op_sel_hi:[1,0]
	v_pk_mul_f32 v[24:25], v[24:25], v[184:185] op_sel_hi:[1,0]
	v_pk_mul_f32 v[26:27], v[26:27], v[184:185] op_sel_hi:[1,0]
	v_pk_mul_f32 v[18:19], v[18:19], v[184:185] op_sel_hi:[1,0]
	v_pk_mul_f32 v[30:31], v[30:31], v[184:185] op_sel_hi:[1,0]
	v_lshl_add_u64 v[64:65], v[96:97], 0, s[20:21]
	s_waitcnt vmcnt(4)
; __device__ __forceinline__ u32x4 pack8(f32x4 a, f32x4 b) { u32x4 w; w.x = pk2(a[0], a[1]); w.y = pk2(a[2], a[3]); w.z = pk2(b[0], b[1]); w.w = pk2(b[2], b[3]); return w; }
;     __device__ __forceinline__ void operator()(const Acc& acc, const pg8::Unit& u, int wid) const {
;     ...
;                     for (int mm = 0; mm < 2; ++mm) { const int s = (row0 + ai * 128 + (2 * mp + mm) * 16) & (SEQ - 1);
; #pragma unroll
;                         for (int n = 0; n < 2; ++n) { c4[mm][n] = *(const f32x4*)(cosT + (size_t)s * 128 + colL + 4 * n); s4[mm][n] = *(const f32x4*)(sinT + (size_t)s * 128 + colL + 4 * n); } }
; #pragma unroll
;                     for (int mm = 0; mm < 2; ++mm) { const int m = 2 * mp + mm, row = row0 + ai * 128 + m * 16;
;                         const float ks = __builtin_amdgcn_rsqf(scv[ai * 4 + m] * (1.f / 1024.f) + EPS) * kmul;
;                         f32x4 o1[2], o2[2];
; #pragma unroll
;                         for (int n = 0; n < 2; ++n) { const f32x4 x1 = acc[ai][0][m][n] * ks, x2 = acc[ai][1][m][n] * ks;
;                             o1[n] = x1 * c4[mm][n] - x2 * s4[mm][n]; o2[n] = x2 * c4[mm][n] + x1 * s4[mm][n]; }
;                         bf16_t* p = QK + (size_t)row * 2048 + pn * 256 + colL;
;                         *(u32x4*)p = pack8(o1[0], o1[1]); *(u32x4*)(p + 128) = pack8(o2[0], o2[1]); }
	v_pk_mul_f32 v[66:67], v[20:21], v[220:221]
	v_pk_mul_f32 v[70:71], v[16:17], v[224:225]
	v_pk_mul_f32 v[68:69], v[22:23], v[222:223]
	v_pk_mul_f32 v[220:221], v[28:29], v[220:221]
	v_pk_mul_f32 v[72:73], v[18:19], v[226:227]
	v_pk_mul_f32 v[224:225], v[24:25], v[224:225]
	v_pk_mul_f32 v[226:227], v[26:27], v[226:227]
	v_pk_fma_f32 v[24:25], v[24:25], v[232:233], v[70:71] neg_lo:[0,0,1] neg_hi:[0,0,1]
	v_pk_mul_f32 v[222:223], v[30:31], v[222:223]
	v_pk_fma_f32 v[30:31], v[30:31], v[230:231], v[68:69] neg_lo:[0,0,1] neg_hi:[0,0,1]
	v_pk_fma_f32 v[28:29], v[28:29], v[228:229], v[66:67] neg_lo:[0,0,1] neg_hi:[0,0,1]
	v_pk_fma_f32 v[20:21], v[20:21], v[228:229], v[220:221]
	v_pk_fma_f32 v[26:27], v[26:27], v[234:235], v[72:73] neg_lo:[0,0,1] neg_hi:[0,0,1]
	v_pk_fma_f32 v[220:221], v[18:19], v[234:235], v[226:227]
	v_cvt_pk_bf16_f32 v18, v24, v25
	v_add_co_u32_e32 v24, vcc, s90, v96
	v_pk_fma_f32 v[22:23], v[22:23], v[230:231], v[222:223]
	v_pk_fma_f32 v[222:223], v[16:17], v[232:233], v[224:225]
	v_cvt_pk_bf16_f32 v16, v28, v29
	v_cvt_pk_bf16_f32 v17, v30, v31
	v_cvt_pk_bf16_f32 v19, v26, v27
	v_addc_co_u32_e32 v25, vcc, 0, v97, vcc
	flat_store_dwordx4 v[24:25], v[16:19]
	s_nop 1
	v_cvt_pk_bf16_f32 v16, v20, v21
	v_cvt_pk_bf16_f32 v17, v22, v23
	v_cvt_pk_bf16_f32 v18, v222, v223
	v_cvt_pk_bf16_f32 v19, v220, v221
	flat_store_dwordx4 v[64:65], v[16:19] offset:256
	s_nop 1
	v_mul_f32_e32 v16, v134, v157
	v_pk_mul_f32 v[4:5], v[4:5], v[16:17] op_sel_hi:[1,0]
	v_pk_mul_f32 v[12:13], v[12:13], v[16:17] op_sel_hi:[1,0]
	v_pk_mul_f32 v[6:7], v[6:7], v[16:17] op_sel_hi:[1,0]
	v_pk_mul_f32 v[18:19], v[4:5], v[236:237]
	v_pk_mul_f32 v[14:15], v[14:15], v[16:17] op_sel_hi:[1,0]
	v_pk_mul_f32 v[20:21], v[6:7], v[238:239]
	v_pk_fma_f32 v[18:19], v[12:13], v[240:241], v[18:19] neg_lo:[0,0,1] neg_hi:[0,0,1]
	v_pk_mul_f32 v[12:13], v[12:13], v[236:237]
	v_pk_mul_f32 v[0:1], v[0:1], v[16:17] op_sel_hi:[1,0]
	v_pk_fma_f32 v[20:21], v[14:15], v[242:243], v[20:21] neg_lo:[0,0,1] neg_hi:[0,0,1]
	v_pk_mul_f32 v[14:15], v[14:15], v[238:239]
	v_pk_fma_f32 v[128:129], v[4:5], v[240:241], v[12:13]
	v_pk_mul_f32 v[4:5], v[8:9], v[16:17] op_sel_hi:[1,0]
	v_pk_mul_f32 v[2:3], v[2:3], v[16:17] op_sel_hi:[1,0]
	v_pk_mul_f32 v[8:9], v[0:1], v[246:247]
	v_pk_fma_f32 v[130:131], v[6:7], v[242:243], v[14:15]
	v_pk_mul_f32 v[6:7], v[10:11], v[16:17] op_sel_hi:[1,0]
	v_pk_mul_f32 v[10:11], v[2:3], v[248:249]
	v_pk_fma_f32 v[8:9], v[4:5], v[250:251], v[8:9] neg_lo:[0,0,1] neg_hi:[0,0,1]
	v_pk_mul_f32 v[4:5], v[4:5], v[246:247]
	v_pk_fma_f32 v[10:11], v[6:7], v[252:253], v[10:11] neg_lo:[0,0,1] neg_hi:[0,0,1]
	v_pk_mul_f32 v[6:7], v[6:7], v[248:249]
	v_pk_fma_f32 v[132:133], v[0:1], v[250:251], v[4:5]
	v_add_co_u32_e32 v4, vcc, 0xb0000, v96
	v_pk_fma_f32 v[134:135], v[2:3], v[252:253], v[6:7]
	v_cvt_pk_bf16_f32 v0, v18, v19
	v_cvt_pk_bf16_f32 v1, v20, v21
	v_cvt_pk_bf16_f32 v2, v8, v9
	v_cvt_pk_bf16_f32 v3, v10, v11
	v_addc_co_u32_e32 v5, vcc, 0, v97, vcc
	flat_store_dwordx4 v[4:5], v[0:3]
